# K-loop edges: pointer selects moved behind the first LDS reads, pointer increments moved out of the MFMA segment tail into the first issue segment
# speedup vs baseline: 1.0014x; 1.0014x over previous
.Llora_n:
	s_add_u32 s10, s78, 0x80
	s_addc_u32 s11, s79, 0
	s_add_u32 s84, s84, 0x100
	s_addc_u32 s85, s85, 0
	s_mov_b32 s78, 0
	v_add_u32_e32 v148, 0x10000, v185
	s_setprio 2
	ds_read_b128 v[128:131], v148 offset:0
	ds_read_b128 v[132:135], v148 offset:1024
	ds_read_b128 v[136:139], v148 offset:2048
	ds_read_b128 v[140:143], v148 offset:3072
	ds_read_b128 v[218:221], v148 offset:16384
	ds_read_b128 v[222:225], v148 offset:17408
	ds_read_b128 v[226:229], v148 offset:18432
	ds_read_b128 v[230:233], v148 offset:19456
	ds_read_b128 v[162:165], v188 offset:0
	ds_read_b128 v[190:193], v188 offset:1024
	ds_read_b128 v[194:197], v188 offset:2048
	ds_read_b128 v[198:201], v188 offset:3072
	ds_read_b128 v[202:205], v188 offset:4096
	ds_read_b128 v[206:209], v188 offset:5120
	ds_read_b128 v[210:213], v188 offset:6144
	ds_read_b128 v[214:217], v188 offset:7168
	s_add_i32 s72, s78, 2
	s_add_u32 s79, s10, 0x80
	s_addc_u32 vcc_lo, s11, 0
	s_cmp_eq_u32 s15, s78
	s_cselect_b32 s78, s12, s84
	s_cselect_b32 vcc_hi, s49, vcc_lo
	s_cselect_b32 vcc_lo, s48, s79
	s_cselect_b32 s79, s13, s85
	s_add_u32 s4, s10, s26
	s_addc_u32 s5, s11, 0
	s_add_i32 m0, s81, 0xc000
	s_nop 0
	global_load_lds_dwordx4 v152, s[4:5]
	s_add_i32 m0, s81, 0xe000
	s_nop 0
	global_load_lds_dwordx4 v144, s[4:5]
	s_add_u32 s10, s10, 0x100
	s_addc_u32 s11, s11, 0
	s_add_u32 s84, s84, 0x100
	s_addc_u32 s85, s85, 0
	s_setprio 0
	s_waitcnt vmcnt(8)
	s_waitcnt lgkmcnt(0)
	s_barrier
	v_mfma_f32_16x16x32_bf16 v[124:127], v[128:131], v[162:165], 0
	v_mfma_f32_16x16x32_bf16 v[116:119], v[136:139], v[162:165], 0
	v_mfma_f32_16x16x32_bf16 v[120:123], v[128:131], v[194:197], 0
	v_mfma_f32_16x16x32_bf16 v[112:115], v[136:139], v[194:197], 0
	v_mfma_f32_16x16x32_bf16 v[92:95], v[128:131], v[202:205], 0
	v_mfma_f32_16x16x32_bf16 v[84:87], v[136:139], v[202:205], 0
	v_mfma_f32_16x16x32_bf16 v[88:91], v[128:131], v[210:213], 0
	v_mfma_f32_16x16x32_bf16 v[80:83], v[136:139], v[210:213], 0
	v_mfma_f32_16x16x32_bf16 v[124:127], v[132:135], v[190:193], v[124:127]
	v_mfma_f32_16x16x32_bf16 v[116:119], v[140:143], v[190:193], v[116:119]
	v_mfma_f32_16x16x32_bf16 v[120:123], v[132:135], v[198:201], v[120:123]
	v_mfma_f32_16x16x32_bf16 v[112:115], v[140:143], v[198:201], v[112:115]
	v_mfma_f32_16x16x32_bf16 v[92:95], v[132:135], v[206:209], v[92:95]
	v_mfma_f32_16x16x32_bf16 v[84:87], v[140:143], v[206:209], v[84:87]
	v_mfma_f32_16x16x32_bf16 v[88:91], v[132:135], v[214:217], v[88:91]
	v_mfma_f32_16x16x32_bf16 v[80:83], v[140:143], v[214:217], v[80:83]
	v_mfma_f32_16x16x32_bf16 v[108:111], v[218:221], v[162:165], 0
	v_mfma_f32_16x16x32_bf16 v[100:103], v[226:229], v[162:165], 0
	v_mfma_f32_16x16x32_bf16 v[104:107], v[218:221], v[194:197], 0
	v_mfma_f32_16x16x32_bf16 v[96:99], v[226:229], v[194:197], 0
	v_mfma_f32_16x16x32_bf16 v[76:79], v[218:221], v[202:205], 0
	v_mfma_f32_16x16x32_bf16 v[68:71], v[226:229], v[202:205], 0
	v_mfma_f32_16x16x32_bf16 v[72:75], v[218:221], v[210:213], 0
	v_mfma_f32_16x16x32_bf16 v[64:67], v[226:229], v[210:213], 0
	v_mfma_f32_16x16x32_bf16 v[108:111], v[222:225], v[190:193], v[108:111]
	v_mfma_f32_16x16x32_bf16 v[100:103], v[230:233], v[190:193], v[100:103]
	v_mfma_f32_16x16x32_bf16 v[104:107], v[222:225], v[198:201], v[104:107]
	v_mfma_f32_16x16x32_bf16 v[96:99], v[230:233], v[198:201], v[96:99]
	v_mfma_f32_16x16x32_bf16 v[76:79], v[222:225], v[206:209], v[76:79]
	v_mfma_f32_16x16x32_bf16 v[68:71], v[230:233], v[206:209], v[68:71]
	v_mfma_f32_16x16x32_bf16 v[72:75], v[222:225], v[214:217], v[72:75]
	v_mfma_f32_16x16x32_bf16 v[64:67], v[230:233], v[214:217], v[64:67]
	s_barrier
	s_setprio 2
	ds_read_b128 v[162:165], v188 offset:16384
	ds_read_b128 v[190:193], v188 offset:17408
	ds_read_b128 v[194:197], v188 offset:18432
	ds_read_b128 v[198:201], v188 offset:19456
	ds_read_b128 v[202:205], v188 offset:20480
	ds_read_b128 v[206:209], v188 offset:21504
	ds_read_b128 v[210:213], v188 offset:22528
	ds_read_b128 v[214:217], v188 offset:23552
	s_add_i32 m0, s81, 0x10000
	s_nop 0
	global_load_lds_dwordx4 v154, s[78:79]
	s_add_i32 m0, s81, 0x12000
	s_nop 0
	global_load_lds_dwordx4 v146, s[78:79]
	s_add_i32 m0, s81, 0x0
	s_nop 0
	global_load_lds_dwordx4 v152, vcc
	s_add_i32 m0, s81, 0x2000
	s_nop 0
	global_load_lds_dwordx4 v144, vcc
	s_add_u32 s4, s78, s26
	s_addc_u32 s5, s79, 0
	s_add_i32 m0, s81, 0x14000
	s_nop 0
	global_load_lds_dwordx4 v154, s[4:5]
	s_add_i32 m0, s81, 0x16000
	s_nop 0
	global_load_lds_dwordx4 v146, s[4:5]
	s_setprio 0
	s_waitcnt vmcnt(8)
	s_waitcnt lgkmcnt(0)
	s_barrier
	v_mfma_f32_16x16x32_bf16 v[60:63], v[128:131], v[162:165], 0
	v_mfma_f32_16x16x32_bf16 v[56:59], v[136:139], v[162:165], 0
	v_mfma_f32_16x16x32_bf16 v[52:55], v[128:131], v[194:197], 0
	v_mfma_f32_16x16x32_bf16 v[48:51], v[136:139], v[194:197], 0
	v_mfma_f32_16x16x32_bf16 v[28:31], v[128:131], v[202:205], 0
	v_mfma_f32_16x16x32_bf16 v[20:23], v[136:139], v[202:205], 0
	v_mfma_f32_16x16x32_bf16 v[24:27], v[128:131], v[210:213], 0
	v_mfma_f32_16x16x32_bf16 v[16:19], v[136:139], v[210:213], 0
	v_mfma_f32_16x16x32_bf16 v[60:63], v[132:135], v[190:193], v[60:63]
	v_mfma_f32_16x16x32_bf16 v[56:59], v[140:143], v[190:193], v[56:59]
	v_mfma_f32_16x16x32_bf16 v[52:55], v[132:135], v[198:201], v[52:55]
	v_mfma_f32_16x16x32_bf16 v[48:51], v[140:143], v[198:201], v[48:51]
	v_mfma_f32_16x16x32_bf16 v[28:31], v[132:135], v[206:209], v[28:31]
	v_mfma_f32_16x16x32_bf16 v[20:23], v[140:143], v[206:209], v[20:23]
	v_mfma_f32_16x16x32_bf16 v[24:27], v[132:135], v[214:217], v[24:27]
	v_mfma_f32_16x16x32_bf16 v[16:19], v[140:143], v[214:217], v[16:19]
	v_mfma_f32_16x16x32_bf16 v[44:47], v[218:221], v[162:165], 0
	v_mfma_f32_16x16x32_bf16 v[36:39], v[226:229], v[162:165], 0
	v_mfma_f32_16x16x32_bf16 v[40:43], v[218:221], v[194:197], 0
	v_mfma_f32_16x16x32_bf16 v[32:35], v[226:229], v[194:197], 0
	v_mfma_f32_16x16x32_bf16 v[12:15], v[218:221], v[202:205], 0
	v_mfma_f32_16x16x32_bf16 v[4:7], v[226:229], v[202:205], 0
	v_mfma_f32_16x16x32_bf16 v[8:11], v[218:221], v[210:213], 0
	v_mfma_f32_16x16x32_bf16 v[0:3], v[226:229], v[210:213], 0
	v_mfma_f32_16x16x32_bf16 v[44:47], v[222:225], v[190:193], v[44:47]
	v_mfma_f32_16x16x32_bf16 v[36:39], v[230:233], v[190:193], v[36:39]
	v_mfma_f32_16x16x32_bf16 v[40:43], v[222:225], v[198:201], v[40:43]
	v_mfma_f32_16x16x32_bf16 v[32:35], v[230:233], v[198:201], v[32:35]
	v_mfma_f32_16x16x32_bf16 v[12:15], v[222:225], v[206:209], v[12:15]
	v_mfma_f32_16x16x32_bf16 v[4:7], v[230:233], v[206:209], v[4:7]
	v_mfma_f32_16x16x32_bf16 v[8:11], v[222:225], v[214:217], v[8:11]
	v_mfma_f32_16x16x32_bf16 v[0:3], v[230:233], v[214:217], v[0:3]
	s_barrier
	s_setprio 2
	ds_read_b128 v[128:131], v148 offset:32768
	ds_read_b128 v[132:135], v148 offset:33792
	ds_read_b128 v[136:139], v148 offset:34816
	ds_read_b128 v[140:143], v148 offset:35840
	ds_read_b128 v[218:221], v148 offset:49152
	ds_read_b128 v[222:225], v148 offset:50176
	ds_read_b128 v[226:229], v148 offset:51200
	ds_read_b128 v[230:233], v148 offset:52224
	ds_read_b128 v[162:165], v188 offset:32768
	ds_read_b128 v[190:193], v188 offset:33792
	ds_read_b128 v[194:197], v188 offset:34816
	ds_read_b128 v[198:201], v188 offset:35840
	ds_read_b128 v[202:205], v188 offset:36864
	ds_read_b128 v[206:209], v188 offset:37888
	ds_read_b128 v[210:213], v188 offset:38912
	ds_read_b128 v[214:217], v188 offset:39936
	s_add_u32 s4, vcc_lo, s26
	s_addc_u32 s5, vcc_hi, 0
	s_add_i32 m0, s81, 0x4000
	s_nop 0
	global_load_lds_dwordx4 v152, s[4:5]
	s_add_i32 m0, s81, 0x6000
	s_nop 0
	global_load_lds_dwordx4 v144, s[4:5]
	s_setprio 0
	s_waitcnt vmcnt(8)
	s_waitcnt lgkmcnt(0)
	s_barrier
	v_mfma_f32_16x16x32_bf16 v[124:127], v[128:131], v[162:165], v[124:127]
	v_mfma_f32_16x16x32_bf16 v[116:119], v[136:139], v[162:165], v[116:119]
	v_mfma_f32_16x16x32_bf16 v[120:123], v[128:131], v[194:197], v[120:123]
	v_mfma_f32_16x16x32_bf16 v[112:115], v[136:139], v[194:197], v[112:115]
	v_mfma_f32_16x16x32_bf16 v[92:95], v[128:131], v[202:205], v[92:95]
	v_mfma_f32_16x16x32_bf16 v[84:87], v[136:139], v[202:205], v[84:87]
	v_mfma_f32_16x16x32_bf16 v[88:91], v[128:131], v[210:213], v[88:91]
	v_mfma_f32_16x16x32_bf16 v[80:83], v[136:139], v[210:213], v[80:83]
	v_mfma_f32_16x16x32_bf16 v[124:127], v[132:135], v[190:193], v[124:127]
	v_mfma_f32_16x16x32_bf16 v[116:119], v[140:143], v[190:193], v[116:119]
	v_mfma_f32_16x16x32_bf16 v[120:123], v[132:135], v[198:201], v[120:123]
	v_mfma_f32_16x16x32_bf16 v[112:115], v[140:143], v[198:201], v[112:115]
	v_mfma_f32_16x16x32_bf16 v[92:95], v[132:135], v[206:209], v[92:95]
	v_mfma_f32_16x16x32_bf16 v[84:87], v[140:143], v[206:209], v[84:87]
	v_mfma_f32_16x16x32_bf16 v[88:91], v[132:135], v[214:217], v[88:91]
	v_mfma_f32_16x16x32_bf16 v[80:83], v[140:143], v[214:217], v[80:83]
	v_mfma_f32_16x16x32_bf16 v[108:111], v[218:221], v[162:165], v[108:111]
	v_mfma_f32_16x16x32_bf16 v[100:103], v[226:229], v[162:165], v[100:103]
	v_mfma_f32_16x16x32_bf16 v[104:107], v[218:221], v[194:197], v[104:107]
	v_mfma_f32_16x16x32_bf16 v[96:99], v[226:229], v[194:197], v[96:99]
	v_mfma_f32_16x16x32_bf16 v[76:79], v[218:221], v[202:205], v[76:79]
	v_mfma_f32_16x16x32_bf16 v[68:71], v[226:229], v[202:205], v[68:71]
	v_mfma_f32_16x16x32_bf16 v[72:75], v[218:221], v[210:213], v[72:75]
	v_mfma_f32_16x16x32_bf16 v[64:67], v[226:229], v[210:213], v[64:67]
	v_mfma_f32_16x16x32_bf16 v[108:111], v[222:225], v[190:193], v[108:111]
	v_mfma_f32_16x16x32_bf16 v[100:103], v[230:233], v[190:193], v[100:103]
	v_mfma_f32_16x16x32_bf16 v[104:107], v[222:225], v[198:201], v[104:107]
	v_mfma_f32_16x16x32_bf16 v[96:99], v[230:233], v[198:201], v[96:99]
	v_mfma_f32_16x16x32_bf16 v[76:79], v[222:225], v[206:209], v[76:79]
	v_mfma_f32_16x16x32_bf16 v[68:71], v[230:233], v[206:209], v[68:71]
	v_mfma_f32_16x16x32_bf16 v[72:75], v[222:225], v[214:217], v[72:75]
	v_mfma_f32_16x16x32_bf16 v[64:67], v[230:233], v[214:217], v[64:67]
	s_barrier
	s_setprio 2
	ds_read_b128 v[162:165], v188 offset:49152
	ds_read_b128 v[190:193], v188 offset:50176
	ds_read_b128 v[194:197], v188 offset:51200
	ds_read_b128 v[198:201], v188 offset:52224
	ds_read_b128 v[202:205], v188 offset:53248
	ds_read_b128 v[206:209], v188 offset:54272
	ds_read_b128 v[210:213], v188 offset:55296
	ds_read_b128 v[214:217], v188 offset:56320
	s_add_u32 s4, s78, 0x80
	s_addc_u32 s5, s79, 0
	s_add_i32 m0, s81, 0x18000
	s_nop 0
	global_load_lds_dwordx4 v154, s[4:5]
	s_add_i32 m0, s81, 0x1a000
	s_nop 0
	global_load_lds_dwordx4 v146, s[4:5]
	s_add_u32 s4, vcc_lo, 0x80
	s_addc_u32 s5, vcc_hi, 0
	s_add_i32 m0, s81, 0x8000
	s_nop 0
	global_load_lds_dwordx4 v152, s[4:5]
	s_add_i32 m0, s81, 0xa000
	s_nop 0
	global_load_lds_dwordx4 v144, s[4:5]
	s_add_u32 s4, s78, s26
	s_addc_u32 s5, s79, 0
	s_add_u32 s4, s4, 0x80
	s_addc_u32 s5, s5, 0
	s_add_i32 m0, s81, 0x1c000
	s_nop 0
	global_load_lds_dwordx4 v154, s[4:5]
	s_add_i32 m0, s81, 0x1e000
	s_nop 0
	global_load_lds_dwordx4 v146, s[4:5]
	s_setprio 0
	s_waitcnt vmcnt(8)
	s_waitcnt lgkmcnt(0)
	s_barrier
	v_mfma_f32_16x16x32_bf16 v[60:63], v[128:131], v[162:165], v[60:63]
	v_mfma_f32_16x16x32_bf16 v[56:59], v[136:139], v[162:165], v[56:59]
	v_mfma_f32_16x16x32_bf16 v[52:55], v[128:131], v[194:197], v[52:55]
	v_mfma_f32_16x16x32_bf16 v[48:51], v[136:139], v[194:197], v[48:51]
	v_mfma_f32_16x16x32_bf16 v[28:31], v[128:131], v[202:205], v[28:31]
	v_mfma_f32_16x16x32_bf16 v[20:23], v[136:139], v[202:205], v[20:23]
	v_mfma_f32_16x16x32_bf16 v[24:27], v[128:131], v[210:213], v[24:27]
	v_mfma_f32_16x16x32_bf16 v[16:19], v[136:139], v[210:213], v[16:19]
	v_mfma_f32_16x16x32_bf16 v[60:63], v[132:135], v[190:193], v[60:63]
	v_mfma_f32_16x16x32_bf16 v[56:59], v[140:143], v[190:193], v[56:59]
	v_mfma_f32_16x16x32_bf16 v[52:55], v[132:135], v[198:201], v[52:55]
	v_mfma_f32_16x16x32_bf16 v[48:51], v[140:143], v[198:201], v[48:51]
	v_mfma_f32_16x16x32_bf16 v[28:31], v[132:135], v[206:209], v[28:31]
	v_mfma_f32_16x16x32_bf16 v[20:23], v[140:143], v[206:209], v[20:23]
	v_mfma_f32_16x16x32_bf16 v[24:27], v[132:135], v[214:217], v[24:27]
	v_mfma_f32_16x16x32_bf16 v[16:19], v[140:143], v[214:217], v[16:19]
	v_mfma_f32_16x16x32_bf16 v[44:47], v[218:221], v[162:165], v[44:47]
	v_mfma_f32_16x16x32_bf16 v[36:39], v[226:229], v[162:165], v[36:39]
	v_mfma_f32_16x16x32_bf16 v[40:43], v[218:221], v[194:197], v[40:43]
	v_mfma_f32_16x16x32_bf16 v[32:35], v[226:229], v[194:197], v[32:35]
	v_mfma_f32_16x16x32_bf16 v[12:15], v[218:221], v[202:205], v[12:15]
	v_mfma_f32_16x16x32_bf16 v[4:7], v[226:229], v[202:205], v[4:7]
	v_mfma_f32_16x16x32_bf16 v[8:11], v[218:221], v[210:213], v[8:11]
	v_mfma_f32_16x16x32_bf16 v[0:3], v[226:229], v[210:213], v[0:3]
	v_mfma_f32_16x16x32_bf16 v[44:47], v[222:225], v[190:193], v[44:47]
	v_mfma_f32_16x16x32_bf16 v[36:39], v[230:233], v[190:193], v[36:39]
	v_mfma_f32_16x16x32_bf16 v[40:43], v[222:225], v[198:201], v[40:43]
	v_mfma_f32_16x16x32_bf16 v[32:35], v[230:233], v[198:201], v[32:35]
	v_mfma_f32_16x16x32_bf16 v[12:15], v[222:225], v[206:209], v[12:15]
	v_mfma_f32_16x16x32_bf16 v[4:7], v[230:233], v[206:209], v[4:7]
	v_mfma_f32_16x16x32_bf16 v[8:11], v[222:225], v[214:217], v[8:11]
	v_mfma_f32_16x16x32_bf16 v[0:3], v[230:233], v[214:217], v[0:3]
	s_cmp_ge_u32 s72, s76
	s_mov_b32 s78, s72
	s_barrier
	s_cbranch_scc1 .Lkloop_done
	.p2align 6
.LBB0_522:
	v_add_u32_e32 v148, 0x10000, v185
	s_setprio 2
	ds_read_b128 v[128:131], v148 offset:0
	ds_read_b128 v[132:135], v148 offset:1024
	ds_read_b128 v[136:139], v148 offset:2048
	ds_read_b128 v[140:143], v148 offset:3072
	ds_read_b128 v[218:221], v148 offset:16384
	ds_read_b128 v[222:225], v148 offset:17408
	ds_read_b128 v[226:229], v148 offset:18432
	ds_read_b128 v[230:233], v148 offset:19456
	ds_read_b128 v[162:165], v188 offset:0
	ds_read_b128 v[190:193], v188 offset:1024
	ds_read_b128 v[194:197], v188 offset:2048
	ds_read_b128 v[198:201], v188 offset:3072
	ds_read_b128 v[202:205], v188 offset:4096
	ds_read_b128 v[206:209], v188 offset:5120
	ds_read_b128 v[210:213], v188 offset:6144
	ds_read_b128 v[214:217], v188 offset:7168
	s_add_i32 s72, s78, 2
	s_add_u32 s79, s10, 0x80
	s_addc_u32 vcc_lo, s11, 0
	s_cmp_eq_u32 s15, s78
	s_cselect_b32 s78, s12, s84
	s_cselect_b32 vcc_hi, s49, vcc_lo
	s_cselect_b32 vcc_lo, s48, s79
	s_cselect_b32 s79, s13, s85
	s_add_u32 s4, s10, s26
	s_addc_u32 s5, s11, 0
	s_add_i32 m0, s81, 0xc000
	s_nop 0
	global_load_lds_dwordx4 v152, s[4:5]
	s_add_i32 m0, s81, 0xe000
	s_nop 0
	global_load_lds_dwordx4 v144, s[4:5]
	s_add_u32 s10, s10, 0x100
	s_addc_u32 s11, s11, 0
	s_add_u32 s84, s84, 0x100
	s_addc_u32 s85, s85, 0
	s_setprio 0
	s_waitcnt vmcnt(8)
	s_waitcnt lgkmcnt(0)
	s_barrier
	v_mfma_f32_16x16x32_bf16 v[124:127], v[128:131], v[162:165], v[124:127]
	v_mfma_f32_16x16x32_bf16 v[116:119], v[136:139], v[162:165], v[116:119]
	v_mfma_f32_16x16x32_bf16 v[120:123], v[128:131], v[194:197], v[120:123]
	v_mfma_f32_16x16x32_bf16 v[112:115], v[136:139], v[194:197], v[112:115]
	v_mfma_f32_16x16x32_bf16 v[92:95], v[128:131], v[202:205], v[92:95]
	v_mfma_f32_16x16x32_bf16 v[84:87], v[136:139], v[202:205], v[84:87]
	v_mfma_f32_16x16x32_bf16 v[88:91], v[128:131], v[210:213], v[88:91]
	v_mfma_f32_16x16x32_bf16 v[80:83], v[136:139], v[210:213], v[80:83]
	v_mfma_f32_16x16x32_bf16 v[124:127], v[132:135], v[190:193], v[124:127]
	v_mfma_f32_16x16x32_bf16 v[116:119], v[140:143], v[190:193], v[116:119]
	v_mfma_f32_16x16x32_bf16 v[120:123], v[132:135], v[198:201], v[120:123]
	v_mfma_f32_16x16x32_bf16 v[112:115], v[140:143], v[198:201], v[112:115]
	v_mfma_f32_16x16x32_bf16 v[92:95], v[132:135], v[206:209], v[92:95]
	v_mfma_f32_16x16x32_bf16 v[84:87], v[140:143], v[206:209], v[84:87]
	v_mfma_f32_16x16x32_bf16 v[88:91], v[132:135], v[214:217], v[88:91]
	v_mfma_f32_16x16x32_bf16 v[80:83], v[140:143], v[214:217], v[80:83]
	v_mfma_f32_16x16x32_bf16 v[108:111], v[218:221], v[162:165], v[108:111]
	v_mfma_f32_16x16x32_bf16 v[100:103], v[226:229], v[162:165], v[100:103]
	v_mfma_f32_16x16x32_bf16 v[104:107], v[218:221], v[194:197], v[104:107]
	v_mfma_f32_16x16x32_bf16 v[96:99], v[226:229], v[194:197], v[96:99]
	v_mfma_f32_16x16x32_bf16 v[76:79], v[218:221], v[202:205], v[76:79]
	v_mfma_f32_16x16x32_bf16 v[68:71], v[226:229], v[202:205], v[68:71]
	v_mfma_f32_16x16x32_bf16 v[72:75], v[218:221], v[210:213], v[72:75]
	v_mfma_f32_16x16x32_bf16 v[64:67], v[226:229], v[210:213], v[64:67]
	v_mfma_f32_16x16x32_bf16 v[108:111], v[222:225], v[190:193], v[108:111]
	v_mfma_f32_16x16x32_bf16 v[100:103], v[230:233], v[190:193], v[100:103]
	v_mfma_f32_16x16x32_bf16 v[104:107], v[222:225], v[198:201], v[104:107]
	v_mfma_f32_16x16x32_bf16 v[96:99], v[230:233], v[198:201], v[96:99]
	v_mfma_f32_16x16x32_bf16 v[76:79], v[222:225], v[206:209], v[76:79]
	v_mfma_f32_16x16x32_bf16 v[68:71], v[230:233], v[206:209], v[68:71]
	v_mfma_f32_16x16x32_bf16 v[72:75], v[222:225], v[214:217], v[72:75]
	v_mfma_f32_16x16x32_bf16 v[64:67], v[230:233], v[214:217], v[64:67]
	s_barrier
	s_setprio 2
	ds_read_b128 v[162:165], v188 offset:16384
	ds_read_b128 v[190:193], v188 offset:17408
	ds_read_b128 v[194:197], v188 offset:18432
	ds_read_b128 v[198:201], v188 offset:19456
	ds_read_b128 v[202:205], v188 offset:20480
	ds_read_b128 v[206:209], v188 offset:21504
	ds_read_b128 v[210:213], v188 offset:22528
	ds_read_b128 v[214:217], v188 offset:23552
	s_add_i32 m0, s81, 0x10000
	s_nop 0
	global_load_lds_dwordx4 v154, s[78:79]
	s_add_i32 m0, s81, 0x12000
	s_nop 0
	global_load_lds_dwordx4 v146, s[78:79]
	s_add_i32 m0, s81, 0x0
	s_nop 0
	global_load_lds_dwordx4 v152, vcc
	s_add_i32 m0, s81, 0x2000
	s_nop 0
	global_load_lds_dwordx4 v144, vcc
	s_add_u32 s4, s78, s26
	s_addc_u32 s5, s79, 0
	s_add_i32 m0, s81, 0x14000
	s_nop 0
	global_load_lds_dwordx4 v154, s[4:5]
	s_add_i32 m0, s81, 0x16000
	s_nop 0
	global_load_lds_dwordx4 v146, s[4:5]
	s_setprio 0
	s_waitcnt vmcnt(8)
	s_waitcnt lgkmcnt(0)
	s_barrier
	v_mfma_f32_16x16x32_bf16 v[60:63], v[128:131], v[162:165], v[60:63]
	v_mfma_f32_16x16x32_bf16 v[56:59], v[136:139], v[162:165], v[56:59]
	v_mfma_f32_16x16x32_bf16 v[52:55], v[128:131], v[194:197], v[52:55]
	v_mfma_f32_16x16x32_bf16 v[48:51], v[136:139], v[194:197], v[48:51]
	v_mfma_f32_16x16x32_bf16 v[28:31], v[128:131], v[202:205], v[28:31]
	v_mfma_f32_16x16x32_bf16 v[20:23], v[136:139], v[202:205], v[20:23]
	v_mfma_f32_16x16x32_bf16 v[24:27], v[128:131], v[210:213], v[24:27]
	v_mfma_f32_16x16x32_bf16 v[16:19], v[136:139], v[210:213], v[16:19]
	v_mfma_f32_16x16x32_bf16 v[60:63], v[132:135], v[190:193], v[60:63]
	v_mfma_f32_16x16x32_bf16 v[56:59], v[140:143], v[190:193], v[56:59]
	v_mfma_f32_16x16x32_bf16 v[52:55], v[132:135], v[198:201], v[52:55]
	v_mfma_f32_16x16x32_bf16 v[48:51], v[140:143], v[198:201], v[48:51]
	v_mfma_f32_16x16x32_bf16 v[28:31], v[132:135], v[206:209], v[28:31]
	v_mfma_f32_16x16x32_bf16 v[20:23], v[140:143], v[206:209], v[20:23]
	v_mfma_f32_16x16x32_bf16 v[24:27], v[132:135], v[214:217], v[24:27]
	v_mfma_f32_16x16x32_bf16 v[16:19], v[140:143], v[214:217], v[16:19]
	v_mfma_f32_16x16x32_bf16 v[44:47], v[218:221], v[162:165], v[44:47]
	v_mfma_f32_16x16x32_bf16 v[36:39], v[226:229], v[162:165], v[36:39]
	v_mfma_f32_16x16x32_bf16 v[40:43], v[218:221], v[194:197], v[40:43]
	v_mfma_f32_16x16x32_bf16 v[32:35], v[226:229], v[194:197], v[32:35]
	v_mfma_f32_16x16x32_bf16 v[12:15], v[218:221], v[202:205], v[12:15]
	v_mfma_f32_16x16x32_bf16 v[4:7], v[226:229], v[202:205], v[4:7]
	v_mfma_f32_16x16x32_bf16 v[8:11], v[218:221], v[210:213], v[8:11]
	v_mfma_f32_16x16x32_bf16 v[0:3], v[226:229], v[210:213], v[0:3]
	v_mfma_f32_16x16x32_bf16 v[44:47], v[222:225], v[190:193], v[44:47]
	v_mfma_f32_16x16x32_bf16 v[36:39], v[230:233], v[190:193], v[36:39]
	v_mfma_f32_16x16x32_bf16 v[40:43], v[222:225], v[198:201], v[40:43]
	v_mfma_f32_16x16x32_bf16 v[32:35], v[230:233], v[198:201], v[32:35]
	v_mfma_f32_16x16x32_bf16 v[12:15], v[222:225], v[206:209], v[12:15]
	v_mfma_f32_16x16x32_bf16 v[4:7], v[230:233], v[206:209], v[4:7]
	v_mfma_f32_16x16x32_bf16 v[8:11], v[222:225], v[214:217], v[8:11]
	v_mfma_f32_16x16x32_bf16 v[0:3], v[230:233], v[214:217], v[0:3]
	s_barrier
	s_setprio 2
	ds_read_b128 v[128:131], v148 offset:32768
	ds_read_b128 v[132:135], v148 offset:33792
	ds_read_b128 v[136:139], v148 offset:34816
	ds_read_b128 v[140:143], v148 offset:35840
	ds_read_b128 v[218:221], v148 offset:49152
	ds_read_b128 v[222:225], v148 offset:50176
	ds_read_b128 v[226:229], v148 offset:51200
	ds_read_b128 v[230:233], v148 offset:52224
	ds_read_b128 v[162:165], v188 offset:32768
	ds_read_b128 v[190:193], v188 offset:33792
	ds_read_b128 v[194:197], v188 offset:34816
	ds_read_b128 v[198:201], v188 offset:35840
	ds_read_b128 v[202:205], v188 offset:36864
	ds_read_b128 v[206:209], v188 offset:37888
	ds_read_b128 v[210:213], v188 offset:38912
	ds_read_b128 v[214:217], v188 offset:39936
	s_add_u32 s4, vcc_lo, s26
	s_addc_u32 s5, vcc_hi, 0
	s_add_i32 m0, s81, 0x4000
	s_nop 0
	global_load_lds_dwordx4 v152, s[4:5]
	s_add_i32 m0, s81, 0x6000
	s_nop 0
	global_load_lds_dwordx4 v144, s[4:5]
	s_setprio 0
	s_waitcnt vmcnt(8)
	s_waitcnt lgkmcnt(0)
	s_barrier
	v_mfma_f32_16x16x32_bf16 v[124:127], v[128:131], v[162:165], v[124:127]
	v_mfma_f32_16x16x32_bf16 v[116:119], v[136:139], v[162:165], v[116:119]
	v_mfma_f32_16x16x32_bf16 v[120:123], v[128:131], v[194:197], v[120:123]
	v_mfma_f32_16x16x32_bf16 v[112:115], v[136:139], v[194:197], v[112:115]
	v_mfma_f32_16x16x32_bf16 v[92:95], v[128:131], v[202:205], v[92:95]
	v_mfma_f32_16x16x32_bf16 v[84:87], v[136:139], v[202:205], v[84:87]
	v_mfma_f32_16x16x32_bf16 v[88:91], v[128:131], v[210:213], v[88:91]
	v_mfma_f32_16x16x32_bf16 v[80:83], v[136:139], v[210:213], v[80:83]
	v_mfma_f32_16x16x32_bf16 v[124:127], v[132:135], v[190:193], v[124:127]
	v_mfma_f32_16x16x32_bf16 v[116:119], v[140:143], v[190:193], v[116:119]
	v_mfma_f32_16x16x32_bf16 v[120:123], v[132:135], v[198:201], v[120:123]
	v_mfma_f32_16x16x32_bf16 v[112:115], v[140:143], v[198:201], v[112:115]
	v_mfma_f32_16x16x32_bf16 v[92:95], v[132:135], v[206:209], v[92:95]
	v_mfma_f32_16x16x32_bf16 v[84:87], v[140:143], v[206:209], v[84:87]
	v_mfma_f32_16x16x32_bf16 v[88:91], v[132:135], v[214:217], v[88:91]
	v_mfma_f32_16x16x32_bf16 v[80:83], v[140:143], v[214:217], v[80:83]
	v_mfma_f32_16x16x32_bf16 v[108:111], v[218:221], v[162:165], v[108:111]
	v_mfma_f32_16x16x32_bf16 v[100:103], v[226:229], v[162:165], v[100:103]
	v_mfma_f32_16x16x32_bf16 v[104:107], v[218:221], v[194:197], v[104:107]
	v_mfma_f32_16x16x32_bf16 v[96:99], v[226:229], v[194:197], v[96:99]
	v_mfma_f32_16x16x32_bf16 v[76:79], v[218:221], v[202:205], v[76:79]
	v_mfma_f32_16x16x32_bf16 v[68:71], v[226:229], v[202:205], v[68:71]
	v_mfma_f32_16x16x32_bf16 v[72:75], v[218:221], v[210:213], v[72:75]
	v_mfma_f32_16x16x32_bf16 v[64:67], v[226:229], v[210:213], v[64:67]
	v_mfma_f32_16x16x32_bf16 v[108:111], v[222:225], v[190:193], v[108:111]
	v_mfma_f32_16x16x32_bf16 v[100:103], v[230:233], v[190:193], v[100:103]
	v_mfma_f32_16x16x32_bf16 v[104:107], v[222:225], v[198:201], v[104:107]
	v_mfma_f32_16x16x32_bf16 v[96:99], v[230:233], v[198:201], v[96:99]
	v_mfma_f32_16x16x32_bf16 v[76:79], v[222:225], v[206:209], v[76:79]
	v_mfma_f32_16x16x32_bf16 v[68:71], v[230:233], v[206:209], v[68:71]
	v_mfma_f32_16x16x32_bf16 v[72:75], v[222:225], v[214:217], v[72:75]
	v_mfma_f32_16x16x32_bf16 v[64:67], v[230:233], v[214:217], v[64:67]
	s_barrier
	s_setprio 2
	ds_read_b128 v[162:165], v188 offset:49152
	ds_read_b128 v[190:193], v188 offset:50176
	ds_read_b128 v[194:197], v188 offset:51200
	ds_read_b128 v[198:201], v188 offset:52224
	ds_read_b128 v[202:205], v188 offset:53248
	ds_read_b128 v[206:209], v188 offset:54272
	ds_read_b128 v[210:213], v188 offset:55296
	ds_read_b128 v[214:217], v188 offset:56320
	s_add_u32 s4, s78, 0x80
	s_addc_u32 s5, s79, 0
	s_add_i32 m0, s81, 0x18000
	s_nop 0
	global_load_lds_dwordx4 v154, s[4:5]
	s_add_i32 m0, s81, 0x1a000
	s_nop 0
	global_load_lds_dwordx4 v146, s[4:5]
	s_add_u32 s4, vcc_lo, 0x80
	s_addc_u32 s5, vcc_hi, 0
	s_add_i32 m0, s81, 0x8000
	s_nop 0
	global_load_lds_dwordx4 v152, s[4:5]
	s_add_i32 m0, s81, 0xa000
	s_nop 0
	global_load_lds_dwordx4 v144, s[4:5]
	s_add_u32 s4, s78, s26
	s_addc_u32 s5, s79, 0
	s_add_u32 s4, s4, 0x80
	s_addc_u32 s5, s5, 0
	s_add_i32 m0, s81, 0x1c000
	s_nop 0
	global_load_lds_dwordx4 v154, s[4:5]
	s_add_i32 m0, s81, 0x1e000
	s_nop 0
	global_load_lds_dwordx4 v146, s[4:5]
	s_setprio 0
	s_waitcnt vmcnt(8)
	s_waitcnt lgkmcnt(0)
	s_barrier
	v_mfma_f32_16x16x32_bf16 v[60:63], v[128:131], v[162:165], v[60:63]
	v_mfma_f32_16x16x32_bf16 v[56:59], v[136:139], v[162:165], v[56:59]
	v_mfma_f32_16x16x32_bf16 v[52:55], v[128:131], v[194:197], v[52:55]
	v_mfma_f32_16x16x32_bf16 v[48:51], v[136:139], v[194:197], v[48:51]
	v_mfma_f32_16x16x32_bf16 v[28:31], v[128:131], v[202:205], v[28:31]
	v_mfma_f32_16x16x32_bf16 v[20:23], v[136:139], v[202:205], v[20:23]
	v_mfma_f32_16x16x32_bf16 v[24:27], v[128:131], v[210:213], v[24:27]
	v_mfma_f32_16x16x32_bf16 v[16:19], v[136:139], v[210:213], v[16:19]
	v_mfma_f32_16x16x32_bf16 v[60:63], v[132:135], v[190:193], v[60:63]
	v_mfma_f32_16x16x32_bf16 v[56:59], v[140:143], v[190:193], v[56:59]
	v_mfma_f32_16x16x32_bf16 v[52:55], v[132:135], v[198:201], v[52:55]
	v_mfma_f32_16x16x32_bf16 v[48:51], v[140:143], v[198:201], v[48:51]
	v_mfma_f32_16x16x32_bf16 v[28:31], v[132:135], v[206:209], v[28:31]
	v_mfma_f32_16x16x32_bf16 v[20:23], v[140:143], v[206:209], v[20:23]
	v_mfma_f32_16x16x32_bf16 v[24:27], v[132:135], v[214:217], v[24:27]
	v_mfma_f32_16x16x32_bf16 v[16:19], v[140:143], v[214:217], v[16:19]
	v_mfma_f32_16x16x32_bf16 v[44:47], v[218:221], v[162:165], v[44:47]
	v_mfma_f32_16x16x32_bf16 v[36:39], v[226:229], v[162:165], v[36:39]
	v_mfma_f32_16x16x32_bf16 v[40:43], v[218:221], v[194:197], v[40:43]
	v_mfma_f32_16x16x32_bf16 v[32:35], v[226:229], v[194:197], v[32:35]
	v_mfma_f32_16x16x32_bf16 v[12:15], v[218:221], v[202:205], v[12:15]
	v_mfma_f32_16x16x32_bf16 v[4:7], v[226:229], v[202:205], v[4:7]
	v_mfma_f32_16x16x32_bf16 v[8:11], v[218:221], v[210:213], v[8:11]
	v_mfma_f32_16x16x32_bf16 v[0:3], v[226:229], v[210:213], v[0:3]
	v_mfma_f32_16x16x32_bf16 v[44:47], v[222:225], v[190:193], v[44:47]
	v_mfma_f32_16x16x32_bf16 v[36:39], v[230:233], v[190:193], v[36:39]
	v_mfma_f32_16x16x32_bf16 v[40:43], v[222:225], v[198:201], v[40:43]
	v_mfma_f32_16x16x32_bf16 v[32:35], v[230:233], v[198:201], v[32:35]
	v_mfma_f32_16x16x32_bf16 v[12:15], v[222:225], v[206:209], v[12:15]
	v_mfma_f32_16x16x32_bf16 v[4:7], v[230:233], v[206:209], v[4:7]
	v_mfma_f32_16x16x32_bf16 v[8:11], v[222:225], v[214:217], v[8:11]
	v_mfma_f32_16x16x32_bf16 v[0:3], v[230:233], v[214:217], v[0:3]
	s_cmp_ge_u32 s72, s76
	s_mov_b32 s78, s72
	s_barrier
	s_cbranch_scc0 .LBB0_522
